# gmlp+pool weight-tile loads issued together (16 in flight) with v_cvt_pk_bf16; gmlp LN reductions via DPP/permlane
# speedup vs baseline: 1.0071x; 1.0071x over previous
.LBB0_669:
	s_lshl_b32 s21, s22, 14
	v_readlane_b32 s22, v251, 39
	s_or_b32 s70, s21, s22
	v_readlane_b32 s44, v253, 12
	s_lshl_b64 s[22:23], s[70:71], 2
	v_readlane_b32 s50, v253, 18
	v_mov_b32_e32 v48, v189
	s_waitcnt lgkmcnt(0)
	s_barrier
	v_readlane_b32 s51, v253, 19
	s_add_u32 s22, s50, s22
	s_addc_u32 s23, s51, s23
	v_and_b32_e32 v8, 15, v48
	v_ashrrev_i32_e32 v9, 4, v48
	v_lshlrev_b32_e32 v160, 5, v8
	v_lshlrev_b32_e32 v2, 7, v9
	v_lshl_add_u64 v[0:1], s[22:23], 0, v[160:161]
	v_ashrrev_i32_e32 v3, 31, v2
	v_lshl_add_u64 v[2:3], v[2:3], 2, v[0:1]
	v_lshl_add_u32 v8, v8, 4, s17
	s_movk_i32 s21, 0x120
	v_mad_u32_u24 v8, v9, s21, v8
	s_mov_b64 s[22:23], 0x2000
	global_load_dwordx4 v[4:7], v[2:3], off
	global_load_dwordx4 v[12:15], v[2:3], off offset:16
	v_lshl_add_u64 v[2:3], v[2:3], 0, s[22:23]
	global_load_dwordx4 v[16:19], v[2:3], off
	global_load_dwordx4 v[20:23], v[2:3], off offset:16
	v_lshl_add_u64 v[2:3], v[2:3], 0, s[22:23]
	global_load_dwordx4 v[24:27], v[2:3], off
	global_load_dwordx4 v[28:31], v[2:3], off offset:16
	v_lshl_add_u64 v[2:3], v[2:3], 0, s[22:23]
	global_load_dwordx4 v[32:35], v[2:3], off
	global_load_dwordx4 v[36:39], v[2:3], off offset:16
	v_lshl_add_u64 v[2:3], v[2:3], 0, s[22:23]
	global_load_dwordx4 v[40:43], v[2:3], off
	global_load_dwordx4 v[44:47], v[2:3], off offset:16
	v_lshl_add_u64 v[2:3], v[2:3], 0, s[22:23]
	global_load_dwordx4 v[48:51], v[2:3], off
	global_load_dwordx4 v[52:55], v[2:3], off offset:16
	v_lshl_add_u64 v[2:3], v[2:3], 0, s[22:23]
	global_load_dwordx4 v[56:59], v[2:3], off
	global_load_dwordx4 v[60:63], v[2:3], off offset:16
	v_lshl_add_u64 v[2:3], v[2:3], 0, s[22:23]
	global_load_dwordx4 v[64:67], v[2:3], off
	global_load_dwordx4 v[68:71], v[2:3], off offset:16
	v_ashrrev_i32_e32 v3, 6, v11
	s_mov_b32 s36, 0xcc00000
	v_readlane_b32 s45, v253, 13
	v_readlane_b32 s46, v253, 14
	v_readlane_b32 s47, v253, 15
	v_readlane_b32 s48, v253, 16
	v_readlane_b32 s49, v253, 17
	v_readlane_b32 s52, v253, 20
	v_readlane_b32 s53, v253, 21
	v_readlane_b32 s54, v253, 22
	v_readlane_b32 s55, v253, 23
	v_readlane_b32 s56, v253, 24
	v_readlane_b32 s57, v253, 25
	v_readlane_b32 s58, v253, 26
	v_readlane_b32 s59, v253, 27
	s_waitcnt vmcnt(14)
	v_cvt_pk_bf16_f32 v4, v4, v5
	v_cvt_pk_bf16_f32 v5, v6, v7
	v_cvt_pk_bf16_f32 v6, v12, v13
	v_cvt_pk_bf16_f32 v7, v14, v15
	ds_write_b128 v8, v[4:7]
	s_waitcnt vmcnt(12)
	v_cvt_pk_bf16_f32 v16, v16, v17
	v_cvt_pk_bf16_f32 v17, v18, v19
	v_cvt_pk_bf16_f32 v18, v20, v21
	v_cvt_pk_bf16_f32 v19, v22, v23
	ds_write_b128 v8, v[16:19] offset:4608
	s_waitcnt vmcnt(10)
	v_cvt_pk_bf16_f32 v24, v24, v25
	v_cvt_pk_bf16_f32 v25, v26, v27
	v_cvt_pk_bf16_f32 v26, v28, v29
	v_cvt_pk_bf16_f32 v27, v30, v31
	ds_write_b128 v8, v[24:27] offset:9216
	s_waitcnt vmcnt(8)
	v_cvt_pk_bf16_f32 v32, v32, v33
	v_cvt_pk_bf16_f32 v33, v34, v35
	v_cvt_pk_bf16_f32 v34, v36, v37
	v_cvt_pk_bf16_f32 v35, v38, v39
	ds_write_b128 v8, v[32:35] offset:13824
	s_waitcnt vmcnt(6)
	v_cvt_pk_bf16_f32 v40, v40, v41
	v_cvt_pk_bf16_f32 v41, v42, v43
	v_cvt_pk_bf16_f32 v42, v44, v45
	v_cvt_pk_bf16_f32 v43, v46, v47
	ds_write_b128 v8, v[40:43] offset:18432
	s_waitcnt vmcnt(4)
	v_cvt_pk_bf16_f32 v48, v48, v49
	v_cvt_pk_bf16_f32 v49, v50, v51
	v_cvt_pk_bf16_f32 v50, v52, v53
	v_cvt_pk_bf16_f32 v51, v54, v55
	ds_write_b128 v8, v[48:51] offset:23040
	s_waitcnt vmcnt(2)
	v_cvt_pk_bf16_f32 v56, v56, v57
	v_cvt_pk_bf16_f32 v57, v58, v59
	v_cvt_pk_bf16_f32 v58, v60, v61
	v_cvt_pk_bf16_f32 v59, v62, v63
	ds_write_b128 v8, v[56:59] offset:27648
	s_waitcnt vmcnt(0)
	v_cvt_pk_bf16_f32 v64, v64, v65
	v_cvt_pk_bf16_f32 v65, v66, v67
	v_cvt_pk_bf16_f32 v66, v68, v69
	v_cvt_pk_bf16_f32 v67, v70, v71
	ds_write_b128 v8, v[64:67] offset:32256
	v_lshrrev_b32_e32 v0, 2, v10
	v_lshrrev_b32_e32 v1, 1, v11
	v_and_or_b32 v0, v1, 24, v0
	v_lshlrev_b32_e32 v1, 3, v11
	v_lshlrev_b32_e32 v8, 5, v3
	v_mul_u32_u24_e32 v0, 0x120, v0
	v_and_b32_e32 v2, 24, v1
	v_or_b32_e32 v4, v8, v10
	s_movk_i32 s21, 0x110
	v_and_b32_e32 v5, 48, v11
	v_add3_u32 v0, v2, s17, v0
	v_mul_lo_u32 v2, v4, s21
	v_add3_u32 v2, s17, v5, v2
	s_waitcnt lgkmcnt(0)
	s_barrier
	ds_read_b128 v[4:7], v2 offset:36864
	ds_read_b128 v[12:15], v2 offset:41216
	v_add_u32_e32 v9, 0x480, v0
	v_add_u32_e32 v32, 32, v0
	v_add_u32_e32 v33, 0x4a0, v0
	v_add_u32_e32 v34, 64, v0
	v_add_u32_e32 v35, 0x4c0, v0
	v_add_u32_e32 v36, 0x60, v0
	v_add_u32_e32 v37, 0x4e0, v0
	ds_read_b64_tr_b16 v[28:29], v0
	ds_read_b64_tr_b16 v[30:31], v9
	ds_read_b64_tr_b16 v[24:25], v32
	ds_read_b64_tr_b16 v[26:27], v33
	ds_read_b64_tr_b16 v[20:21], v34
	ds_read_b64_tr_b16 v[22:23], v35
	ds_read_b64_tr_b16 v[16:17], v36
	ds_read_b64_tr_b16 v[18:19], v37
	s_waitcnt lgkmcnt(0)
	v_add_u32_e32 v9, 0x80, v0
	v_add_u32_e32 v64, 0x500, v0
	v_add_u32_e32 v65, 0xa0, v0
	v_add_u32_e32 v66, 0x520, v0
	v_add_u32_e32 v67, 0xc0, v0
	v_add_u32_e32 v68, 0x540, v0
	v_add_u32_e32 v69, 0xe0, v0
	v_add_u32_e32 v70, 0x560, v0
	ds_read_b64_tr_b16 v[60:61], v9
	ds_read_b64_tr_b16 v[62:63], v64
	ds_read_b64_tr_b16 v[56:57], v65
	ds_read_b64_tr_b16 v[58:59], v66
	ds_read_b64_tr_b16 v[52:53], v67
	ds_read_b64_tr_b16 v[54:55], v68
	ds_read_b64_tr_b16 v[48:49], v69
	ds_read_b64_tr_b16 v[50:51], v70
	s_waitcnt lgkmcnt(0)
	s_waitcnt lgkmcnt(1)
	v_mfma_f32_16x16x32_bf16 v[32:35], v[4:7], v[28:31], 0
	v_add_u32_e32 v9, 0x2400, v0
	v_add_u32_e32 v96, 0x2880, v0
	v_add_u32_e32 v97, 0x2420, v0
	s_waitcnt lgkmcnt(0)
	v_mfma_f32_16x16x32_bf16 v[28:31], v[12:15], v[28:31], 0
	v_add_u32_e32 v98, 0x28a0, v0
	v_add_u32_e32 v99, 0x2440, v0
	v_add_u32_e32 v100, 0x28c0, v0
	v_mfma_f32_16x16x32_bf16 v[36:39], v[4:7], v[24:27], 0
	v_add_u32_e32 v101, 0x2460, v0
	v_add_u32_e32 v102, 0x28e0, v0
	s_movk_i32 s21, 0x4200
	v_mfma_f32_16x16x32_bf16 v[24:27], v[12:15], v[24:27], 0
	v_readlane_b32 s22, v251, 45
	v_mfma_f32_16x16x32_bf16 v[40:43], v[4:7], v[20:23], 0
	v_mfma_f32_16x16x32_bf16 v[20:23], v[12:15], v[20:23], 0
	v_mfma_f32_16x16x32_bf16 v[44:47], v[4:7], v[16:19], 0
	v_mfma_f32_16x16x32_bf16 v[16:19], v[12:15], v[16:19], 0
	v_mfma_f32_16x16x32_bf16 v[64:67], v[4:7], v[60:63], 0
	v_mfma_f32_16x16x32_bf16 v[60:63], v[12:15], v[60:63], 0
	v_mfma_f32_16x16x32_bf16 v[68:71], v[4:7], v[56:59], 0
	v_mfma_f32_16x16x32_bf16 v[56:59], v[12:15], v[56:59], 0
	v_mfma_f32_16x16x32_bf16 v[72:75], v[4:7], v[52:55], 0
	v_mfma_f32_16x16x32_bf16 v[52:55], v[12:15], v[52:55], 0
	v_mfma_f32_16x16x32_bf16 v[4:7], v[4:7], v[48:51], 0
	v_mfma_f32_16x16x32_bf16 v[12:15], v[12:15], v[48:51], 0
	ds_read_b128 v[48:51], v2 offset:36928
	ds_read_b128 v[76:79], v2 offset:41280
	ds_read_b64_tr_b16 v[92:93], v9
	ds_read_b64_tr_b16 v[94:95], v96
	ds_read_b64_tr_b16 v[88:89], v97
	ds_read_b64_tr_b16 v[90:91], v98
	ds_read_b64_tr_b16 v[84:85], v99
	ds_read_b64_tr_b16 v[86:87], v100
	ds_read_b64_tr_b16 v[80:81], v101
	ds_read_b64_tr_b16 v[82:83], v102
	s_waitcnt lgkmcnt(0)
	v_add_u32_e32 v9, 0x2480, v0
	s_waitcnt lgkmcnt(1)
	v_mfma_f32_16x16x32_bf16 v[32:35], v[48:51], v[92:95], v[32:35]
	v_add_u32_e32 v96, 0x2900, v0
	v_add_u32_e32 v97, 0x24a0, v0
	v_add_u32_e32 v98, 0x2920, v0
	s_waitcnt lgkmcnt(0)
	v_mfma_f32_16x16x32_bf16 v[28:31], v[76:79], v[92:95], v[28:31]
	v_add_u32_e32 v99, 0x24c0, v0
	v_add_u32_e32 v100, 0x2940, v0
	v_add_u32_e32 v101, 0x24e0, v0
	v_mfma_f32_16x16x32_bf16 v[36:39], v[48:51], v[88:91], v[36:39]
	v_add_u32_e32 v102, 0x2960, v0
	v_mfma_f32_16x16x32_bf16 v[24:27], v[76:79], v[88:91], v[24:27]
	v_mfma_f32_16x16x32_bf16 v[40:43], v[48:51], v[84:87], v[40:43]
	v_mfma_f32_16x16x32_bf16 v[20:23], v[76:79], v[84:87], v[20:23]
	v_mfma_f32_16x16x32_bf16 v[44:47], v[48:51], v[80:83], v[44:47]
	v_mfma_f32_16x16x32_bf16 v[16:19], v[76:79], v[80:83], v[16:19]
	ds_read_b64_tr_b16 v[92:93], v9
	ds_read_b64_tr_b16 v[94:95], v96
	ds_read_b64_tr_b16 v[88:89], v97
	ds_read_b64_tr_b16 v[90:91], v98
	ds_read_b64_tr_b16 v[84:85], v99
	ds_read_b64_tr_b16 v[86:87], v100
	ds_read_b64_tr_b16 v[80:81], v101
	ds_read_b64_tr_b16 v[82:83], v102
	s_waitcnt lgkmcnt(0)
	v_add_u32_e32 v9, 0x4800, v0
	v_add_u32_e32 v96, 0x4c80, v0
	v_mfma_f32_16x16x32_bf16 v[64:67], v[48:51], v[92:95], v[64:67]
	v_add_u32_e32 v97, 0x4820, v0
	v_add_u32_e32 v98, 0x4ca0, v0
	v_add_u32_e32 v99, 0x4840, v0
	v_mfma_f32_16x16x32_bf16 v[60:63], v[76:79], v[92:95], v[60:63]
	v_add_u32_e32 v100, 0x4cc0, v0
	v_add_u32_e32 v101, 0x4860, v0
	v_add_u32_e32 v102, 0x4ce0, v0
	v_mfma_f32_16x16x32_bf16 v[68:71], v[48:51], v[88:91], v[68:71]
	v_mfma_f32_16x16x32_bf16 v[56:59], v[76:79], v[88:91], v[56:59]
	v_mfma_f32_16x16x32_bf16 v[72:75], v[48:51], v[84:87], v[72:75]
	v_mfma_f32_16x16x32_bf16 v[52:55], v[76:79], v[84:87], v[52:55]
	v_mfma_f32_16x16x32_bf16 v[4:7], v[48:51], v[80:83], v[4:7]
	v_mfma_f32_16x16x32_bf16 v[12:15], v[76:79], v[80:83], v[12:15]
	ds_read_b128 v[48:51], v2 offset:36992
	ds_read_b128 v[76:79], v2 offset:41344
	ds_read_b64_tr_b16 v[92:93], v9
	ds_read_b64_tr_b16 v[94:95], v96
	ds_read_b64_tr_b16 v[88:89], v97
	ds_read_b64_tr_b16 v[90:91], v98
	ds_read_b64_tr_b16 v[84:85], v99
	ds_read_b64_tr_b16 v[86:87], v100
	ds_read_b64_tr_b16 v[80:81], v101
	ds_read_b64_tr_b16 v[82:83], v102
	s_waitcnt lgkmcnt(0)
	v_add_u32_e32 v9, 0x4880, v0
	s_waitcnt lgkmcnt(1)
	v_mfma_f32_16x16x32_bf16 v[32:35], v[48:51], v[92:95], v[32:35]
	v_add_u32_e32 v96, 0x4d00, v0
	v_add_u32_e32 v97, 0x48a0, v0
	v_add_u32_e32 v98, 0x4d20, v0
	s_waitcnt lgkmcnt(0)
	v_mfma_f32_16x16x32_bf16 v[28:31], v[76:79], v[92:95], v[28:31]
	v_add_u32_e32 v99, 0x48c0, v0
	v_add_u32_e32 v100, 0x4d40, v0
	v_add_u32_e32 v101, 0x48e0, v0
	v_mfma_f32_16x16x32_bf16 v[36:39], v[48:51], v[88:91], v[36:39]
	v_add_u32_e32 v102, 0x4d60, v0
	v_mfma_f32_16x16x32_bf16 v[24:27], v[76:79], v[88:91], v[24:27]
	v_mfma_f32_16x16x32_bf16 v[40:43], v[48:51], v[84:87], v[40:43]
	v_mfma_f32_16x16x32_bf16 v[20:23], v[76:79], v[84:87], v[20:23]
	v_mfma_f32_16x16x32_bf16 v[44:47], v[48:51], v[80:83], v[44:47]
	v_mfma_f32_16x16x32_bf16 v[16:19], v[76:79], v[80:83], v[16:19]
	ds_read_b64_tr_b16 v[92:93], v9
	ds_read_b64_tr_b16 v[94:95], v96
	ds_read_b64_tr_b16 v[88:89], v97
	ds_read_b64_tr_b16 v[90:91], v98
	ds_read_b64_tr_b16 v[84:85], v99
	ds_read_b64_tr_b16 v[86:87], v100
	ds_read_b64_tr_b16 v[80:81], v101
	ds_read_b64_tr_b16 v[82:83], v102
	s_waitcnt lgkmcnt(0)
	v_add_u32_e32 v9, 0x7080, v0
	v_add_u32_e32 v96, 0x6c20, v0
	v_mfma_f32_16x16x32_bf16 v[64:67], v[48:51], v[92:95], v[64:67]
	v_add_u32_e32 v97, 0x70a0, v0
	v_add_u32_e32 v98, 0x6c40, v0
	v_add_u32_e32 v99, 0x70c0, v0
	v_mfma_f32_16x16x32_bf16 v[60:63], v[76:79], v[92:95], v[60:63]
	v_add_u32_e32 v100, 0x6c60, v0
	v_add_u32_e32 v101, 0x70e0, v0
	v_mfma_f32_16x16x32_bf16 v[68:71], v[48:51], v[88:91], v[68:71]
	v_mfma_f32_16x16x32_bf16 v[56:59], v[76:79], v[88:91], v[56:59]
	v_mfma_f32_16x16x32_bf16 v[72:75], v[48:51], v[84:87], v[72:75]
	v_mfma_f32_16x16x32_bf16 v[52:55], v[76:79], v[84:87], v[52:55]
	v_mfma_f32_16x16x32_bf16 v[4:7], v[48:51], v[80:83], v[4:7]
	v_mfma_f32_16x16x32_bf16 v[12:15], v[76:79], v[80:83], v[12:15]
	ds_read_b128 v[48:51], v2 offset:37056
	ds_read_b128 v[76:79], v2 offset:41408
	v_add_u32_e32 v2, 0x6c00, v0
	ds_read_b64_tr_b16 v[92:93], v2
	ds_read_b64_tr_b16 v[94:95], v9
	ds_read_b64_tr_b16 v[88:89], v96
	ds_read_b64_tr_b16 v[90:91], v97
	ds_read_b64_tr_b16 v[84:85], v98
	ds_read_b64_tr_b16 v[86:87], v99
	ds_read_b64_tr_b16 v[80:81], v100
	ds_read_b64_tr_b16 v[82:83], v101
	s_waitcnt lgkmcnt(0)
	v_add_u32_e32 v2, 0x6c80, v0
	s_waitcnt lgkmcnt(1)
	v_mfma_f32_16x16x32_bf16 v[32:35], v[48:51], v[92:95], v[32:35]
	v_add_u32_e32 v9, 0x7100, v0
	v_add_u32_e32 v96, 0x6ca0, v0
	v_add_u32_e32 v97, 0x7120, v0
	s_waitcnt lgkmcnt(0)
	v_mfma_f32_16x16x32_bf16 v[28:31], v[76:79], v[92:95], v[28:31]
	v_add_u32_e32 v98, 0x6cc0, v0
	v_add_u32_e32 v99, 0x7140, v0
	v_add_u32_e32 v100, 0x6ce0, v0
	v_mfma_f32_16x16x32_bf16 v[36:39], v[48:51], v[88:91], v[36:39]
	v_add_u32_e32 v0, 0x7160, v0
	v_mfma_f32_16x16x32_bf16 v[24:27], v[76:79], v[88:91], v[24:27]
	v_mfma_f32_16x16x32_bf16 v[40:43], v[48:51], v[84:87], v[40:43]
	v_mfma_f32_16x16x32_bf16 v[20:23], v[76:79], v[84:87], v[20:23]
	v_mfma_f32_16x16x32_bf16 v[44:47], v[48:51], v[80:83], v[44:47]
	v_mfma_f32_16x16x32_bf16 v[16:19], v[76:79], v[80:83], v[16:19]
	ds_read_b64_tr_b16 v[92:93], v2
	ds_read_b64_tr_b16 v[94:95], v9
	ds_read_b64_tr_b16 v[88:89], v96
	ds_read_b64_tr_b16 v[90:91], v97
	ds_read_b64_tr_b16 v[84:85], v98
	ds_read_b64_tr_b16 v[86:87], v99
	ds_read_b64_tr_b16 v[80:81], v100
	ds_read_b64_tr_b16 v[82:83], v0
	s_waitcnt lgkmcnt(0)
	v_mul_lo_u32 v2, v3, s21
	v_lshrrev_b32_e32 v3, 2, v11
	v_and_b32_e32 v3, 12, v3
	v_mul_u32_u24_e32 v3, 0x84, v3
	v_mfma_f32_16x16x32_bf16 v[60:63], v[76:79], v[92:95], v[60:63]
	v_add_u32_e32 v0, s17, v2
	v_lshlrev_b32_e32 v9, 2, v10
	v_lshlrev_b32_e32 v3, 2, v3
	v_mfma_f32_16x16x32_bf16 v[56:59], v[76:79], v[88:91], v[56:59]
	v_add3_u32 v0, v0, v9, v3
	v_add_u32_e32 v3, 0x400, v0
	v_mfma_f32_16x16x32_bf16 v[52:55], v[76:79], v[84:87], v[52:55]
	s_barrier
	ds_write2_b32 v0, v32, v36 offset1:16
	ds_write2_b32 v0, v33, v37 offset0:132 offset1:148
	v_mfma_f32_16x16x32_bf16 v[12:15], v[76:79], v[80:83], v[12:15]
	s_lshl_b32 s21, s43, 2
	s_add_u32 s22, s22, s21
	v_readlane_b32 s21, v251, 46
	v_mfma_f32_16x16x32_bf16 v[4:7], v[48:51], v[80:83], v[4:7]
	s_addc_u32 s23, s21, 0
	s_movk_i32 s21, 0x1000
	v_mfma_f32_16x16x32_bf16 v[64:67], v[48:51], v[92:95], v[64:67]
	v_mfma_f32_16x16x32_bf16 v[68:71], v[48:51], v[88:91], v[68:71]
	v_mfma_f32_16x16x32_bf16 v[72:75], v[48:51], v[84:87], v[72:75]
	ds_write2_b32 v3, v34, v38 offset0:8 offset1:24
	ds_write2_b32 v3, v35, v39 offset0:140 offset1:156
	ds_write2_b32 v0, v40, v44 offset0:32 offset1:48
	ds_write2_b32 v0, v41, v45 offset0:164 offset1:180
	ds_write2_b32 v3, v42, v46 offset0:40 offset1:56
	ds_write2_b32 v3, v43, v47 offset0:172 offset1:188
	s_nop 0
	ds_write2_b32 v0, v64, v68 offset0:64 offset1:80
	ds_write2_b32 v0, v65, v69 offset0:196 offset1:212
	ds_write2_b32 v3, v66, v70 offset0:72 offset1:88
	ds_write2_b32 v3, v67, v71 offset0:204 offset1:220
	ds_write2_b32 v0, v72, v4 offset0:96 offset1:112
	ds_write2_b32 v0, v73, v5 offset0:228 offset1:244
	ds_write2_b32 v3, v74, v6 offset0:104 offset1:120
	ds_write2_b32 v3, v75, v7 offset0:236 offset1:252
	v_add_u32_e32 v3, 0x2000, v0
	v_add_u32_e32 v4, 0x2400, v0
	v_add_u32_e32 v0, 0x2800, v0
	ds_write2_b32 v3, v28, v24 offset0:64 offset1:80
	ds_write2_b32 v3, v29, v25 offset0:196 offset1:212
	ds_write2_b32 v4, v30, v26 offset0:72 offset1:88
	ds_write2_b32 v4, v31, v27 offset0:204 offset1:220
	ds_write2_b32 v3, v20, v16 offset0:96 offset1:112
	ds_write2_b32 v3, v21, v17 offset0:228 offset1:244
	ds_write2_b32 v4, v22, v18 offset0:104 offset1:120
	ds_write2_b32 v4, v23, v19 offset0:236 offset1:252
	ds_write2_b32 v3, v60, v56 offset0:128 offset1:144
	ds_write2_b32 v4, v61, v57 offset0:4 offset1:20
	ds_write2_b32 v4, v62, v58 offset0:136 offset1:152
	ds_write2_b32 v0, v63, v59 offset0:12 offset1:28
	ds_write2_b32 v3, v52, v12 offset0:160 offset1:176
	ds_write2_b32 v4, v53, v13 offset0:36 offset1:52
	ds_write2_b32 v4, v54, v14 offset0:168 offset1:184
	ds_write2_b32 v0, v55, v15 offset0:44 offset1:60
	v_and_b32_e32 v0, 0x78, v1
	v_bfe_u32 v1, v11, 4, 2
	v_add3_u32 v20, v1, s20, v8
	s_movk_i32 s20, 0x210
	v_lshlrev_b32_e32 v160, 2, v0
	v_mad_u32_u24 v1, v1, s20, v2
	v_lshlrev_b32_e32 v2, 5, v10
	v_lshl_add_u64 v[12:13], s[22:23], 0, v[160:161]
	v_add3_u32 v21, v1, v2, s17
	s_mov_b32 s20, 0
	v_lshlrev_b32_e32 v160, 1, v0

.LBB0_673:
	s_andn2_b64 vcc, exec, s[36:37]
	s_cbranch_vccnz .LBB0_695
	s_and_b32 s21, s19, 3
	v_readlane_b32 s23, v251, 40
	s_lshl_b32 s20, s19, 5
	s_or_b32 s23, s21, s23
	s_and_b32 s20, s20, 0xff80
	s_lshl_b32 s70, s23, 14
	v_mov_b32_e32 v43, v189
	v_readlane_b32 s44, v253, 12
	v_mov_b32_e32 v2, v189
	s_add_i32 s22, s20, 0xffff6000
	s_lshl_b64 s[36:37], s[70:71], 2
	v_readlane_b32 s46, v253, 14
	v_readlane_b32 s47, v253, 15
	v_and_b32_e32 v3, 15, v2
	s_add_u32 s36, s46, s36
	v_lshlrev_b32_e32 v160, 5, v3
	v_lshl_add_u32 v8, v3, 4, s17
	v_ashrrev_i32_e32 v3, 4, v2
	s_addc_u32 s37, s47, s37
	v_lshlrev_b32_e32 v4, 7, v3
	v_lshl_add_u64 v[0:1], s[36:37], 0, v[160:161]
	v_ashrrev_i32_e32 v5, 31, v4
	v_lshl_add_u64 v[10:11], v[4:5], 2, v[0:1]
	s_movk_i32 s23, 0x110
	v_mad_u32_u24 v9, v3, s23, v8
	s_mov_b64 s[38:39], 0x2000
	global_load_dwordx4 v[62:65], v[10:11], off
	global_load_dwordx4 v[66:69], v[10:11], off offset:16
	v_lshl_add_u64 v[14:15], v[10:11], 0, s[38:39]
	global_load_dwordx4 v[70:73], v[14:15], off
	global_load_dwordx4 v[74:77], v[14:15], off offset:16
	v_lshl_add_u64 v[16:17], v[14:15], 0, s[38:39]
	global_load_dwordx4 v[78:81], v[16:17], off
	global_load_dwordx4 v[82:85], v[16:17], off offset:16
	v_lshl_add_u64 v[18:19], v[16:17], 0, s[38:39]
	global_load_dwordx4 v[86:89], v[18:19], off
	global_load_dwordx4 v[90:93], v[18:19], off offset:16
	v_lshl_add_u64 v[24:25], v[18:19], 0, s[38:39]
	global_load_dwordx4 v[94:97], v[24:25], off
	global_load_dwordx4 v[98:101], v[24:25], off offset:16
	v_lshl_add_u64 v[26:27], v[24:25], 0, s[38:39]
	global_load_dwordx4 v[32:35], v[26:27], off
	global_load_dwordx4 v[36:39], v[26:27], off offset:16
	v_lshl_add_u64 v[12:13], v[26:27], 0, s[38:39]
	global_load_dwordx4 v[44:47], v[12:13], off
	global_load_dwordx4 v[48:51], v[12:13], off offset:16
	v_lshl_add_u64 v[52:53], v[12:13], 0, s[38:39]
	global_load_dwordx4 v[4:7], v[52:53], off
	global_load_dwordx4 v[20:23], v[52:53], off offset:16
	v_ashrrev_i32_e32 v31, 6, v43
	v_lshlrev_b32_e32 v30, 5, v31
	v_and_b32_e32 v42, 15, v43
	v_and_b32_e32 v28, 63, v43
	v_bfe_u32 v29, v43, 4, 2
	v_readlane_b32 s45, v253, 13
	v_readlane_b32 s48, v253, 16
	v_readlane_b32 s49, v253, 17
	v_readlane_b32 s50, v253, 18
	v_readlane_b32 s51, v253, 19
	v_readlane_b32 s52, v253, 20
	v_readlane_b32 s53, v253, 21
	v_readlane_b32 s54, v253, 22
	v_readlane_b32 s55, v253, 23
	v_readlane_b32 s56, v253, 24
	v_readlane_b32 s57, v253, 25
	v_readlane_b32 s58, v253, 26
	v_readlane_b32 s59, v253, 27
	s_mov_b64 s[38:39], 0
	s_waitcnt vmcnt(14)
	v_cvt_pk_bf16_f32 v62, v62, v63
	v_cvt_pk_bf16_f32 v63, v64, v65
	v_cvt_pk_bf16_f32 v64, v66, v67
	v_cvt_pk_bf16_f32 v65, v68, v69
	ds_write_b128 v9, v[62:65]
	s_waitcnt vmcnt(12)
	v_cvt_pk_bf16_f32 v70, v70, v71
	v_cvt_pk_bf16_f32 v71, v72, v73
	v_cvt_pk_bf16_f32 v72, v74, v75
	v_cvt_pk_bf16_f32 v73, v76, v77
	ds_write_b128 v9, v[70:73] offset:4352
	s_waitcnt vmcnt(10)
	v_cvt_pk_bf16_f32 v78, v78, v79
	v_cvt_pk_bf16_f32 v79, v80, v81
	v_cvt_pk_bf16_f32 v80, v82, v83
	v_cvt_pk_bf16_f32 v81, v84, v85
	ds_write_b128 v9, v[78:81] offset:8704
	s_waitcnt vmcnt(8)
	v_cvt_pk_bf16_f32 v86, v86, v87
	v_cvt_pk_bf16_f32 v87, v88, v89
	v_cvt_pk_bf16_f32 v88, v90, v91
	v_cvt_pk_bf16_f32 v89, v92, v93
	ds_write_b128 v9, v[86:89] offset:13056
	s_waitcnt vmcnt(6)
	v_cvt_pk_bf16_f32 v94, v94, v95
	v_cvt_pk_bf16_f32 v95, v96, v97
	v_cvt_pk_bf16_f32 v96, v98, v99
	v_cvt_pk_bf16_f32 v97, v100, v101
	ds_write_b128 v9, v[94:97] offset:17408
	s_waitcnt vmcnt(4)
	v_cvt_pk_bf16_f32 v32, v32, v33
	v_cvt_pk_bf16_f32 v33, v34, v35
	v_cvt_pk_bf16_f32 v34, v36, v37
	v_cvt_pk_bf16_f32 v35, v38, v39
	ds_write_b128 v9, v[32:35] offset:21760
	s_waitcnt vmcnt(2)
	v_cvt_pk_bf16_f32 v44, v44, v45
	v_cvt_pk_bf16_f32 v45, v46, v47
	v_cvt_pk_bf16_f32 v46, v48, v49
	v_cvt_pk_bf16_f32 v47, v50, v51
	ds_write_b128 v9, v[44:47] offset:26112
	s_waitcnt vmcnt(0)
	v_cvt_pk_bf16_f32 v4, v4, v5
	v_cvt_pk_bf16_f32 v5, v6, v7
	v_cvt_pk_bf16_f32 v6, v20, v21
	v_cvt_pk_bf16_f32 v7, v22, v23
	ds_write_b128 v9, v[4:7] offset:30464
	v_mbcnt_hi_u32_b32 v1, -1, v194
	v_and_b32_e32 v2, 64, v1
	v_add_u32_e32 v2, 64, v2
	v_xor_b32_e32 v3, 32, v1
	v_cmp_lt_i32_e32 vcc, v3, v2
	v_add_u32_e32 v0, s22, v30
	s_movk_i32 s22, 0x2400
	v_cndmask_b32_e32 v3, v1, v3, vcc
	v_lshlrev_b32_e32 v44, 2, v3
	v_xor_b32_e32 v3, 16, v1
	v_cmp_lt_i32_e32 vcc, v3, v2
	v_cmp_eq_u32_e64 s[36:37], s21, v29
	s_nop 0
	v_cndmask_b32_e32 v3, v1, v3, vcc
	v_lshlrev_b32_e32 v45, 2, v3
	v_xor_b32_e32 v3, 8, v1
	v_cmp_lt_i32_e32 vcc, v3, v2
	s_nop 1
	v_cndmask_b32_e32 v3, v1, v3, vcc
	v_lshlrev_b32_e32 v46, 2, v3
	v_xor_b32_e32 v3, 4, v1
	v_cmp_lt_i32_e32 vcc, v3, v2
	s_nop 1
	v_cndmask_b32_e32 v3, v1, v3, vcc
	v_lshlrev_b32_e32 v47, 2, v3
	v_xor_b32_e32 v3, 2, v1
	v_cmp_lt_i32_e32 vcc, v3, v2
	s_nop 1
	v_cndmask_b32_e32 v3, v1, v3, vcc
	v_lshlrev_b32_e32 v48, 2, v3
	v_xor_b32_e32 v3, 1, v1
	v_cmp_lt_i32_e32 vcc, v3, v2
	s_nop 1
	v_cndmask_b32_e32 v1, v1, v3, vcc
	v_lshlrev_b32_e32 v49, 2, v1
	v_mul_lo_u32 v1, v31, s22
	v_lshl_or_b32 v1, v42, 4, v1
	v_readlane_b32 s22, v251, 55
	s_nop 1
	v_add_u32_e32 v50, s22, v1
	v_mad_i64_i32 v[0:1], s[22:23], v0, s0, 0
	v_lshl_or_b32 v0, v28, 4, v0
	v_lshl_add_u64 v[32:33], s[30:31], 0, v[0:1]
	s_branch .LBB0_676

.LBB0_676:
	v_lshl_add_u64 v[4:5], v[32:33], 0, s[38:39]
	v_add_co_u32_e32 v0, vcc, 0x6400000, v4
	s_nop 1
	v_addc_co_u32_e32 v1, vcc, 0, v5, vcc
	global_load_dwordx4 v[0:3], v[0:1], off offset:1024
	v_add_co_u32_e32 v6, vcc, 0x6403000, v4
	s_nop 1
	v_addc_co_u32_e32 v7, vcc, 0, v5, vcc
	global_load_dwordx4 v[24:27], v[6:7], off offset:2048
	v_add_co_u32_e32 v8, vcc, 0x6406000, v4
	s_waitcnt vmcnt(1)
	v_lshlrev_b32_e32 v36, 16, v0
	v_and_b32_e32 v37, 0xffff0000, v0
	v_add_f32_e32 v0, 0, v36
	v_lshlrev_b32_e32 v38, 16, v1
	v_add_f32_e32 v0, v0, v37
	s_waitcnt lgkmcnt(0)
	v_addc_co_u32_e32 v9, vcc, 0, v5, vcc
	v_and_b32_e32 v39, 0xffff0000, v1
	v_add_f32_e32 v0, v0, v38
	v_add_co_u32_e32 v6, vcc, 0x640a000, v4
	v_lshlrev_b32_e32 v40, 16, v2
	v_add_f32_e32 v0, v0, v39
	v_addc_co_u32_e32 v7, vcc, 0, v5, vcc
	v_and_b32_e32 v41, 0xffff0000, v2
	v_add_f32_e32 v0, v0, v40
	v_add_co_u32_e32 v10, vcc, 0x640d000, v4
	v_lshlrev_b32_e32 v52, 16, v3
	v_add_f32_e32 v0, v0, v41
	v_addc_co_u32_e32 v11, vcc, 0, v5, vcc
	v_and_b32_e32 v53, 0xffff0000, v3
	v_add_f32_e32 v0, v0, v52
	global_load_dwordx4 v[20:23], v[8:9], off offset:3072
	global_load_dwordx4 v[16:19], v[6:7], off
	v_add_co_u32_e32 v6, vcc, 0x6410000, v4
	v_add_f32_e32 v2, v0, v53
	s_nop 0
	v_addc_co_u32_e32 v7, vcc, 0, v5, vcc
	v_add_co_u32_e32 v34, vcc, 0x6413000, v4
	global_load_dwordx4 v[12:15], v[10:11], off offset:1024
	s_nop 0
	global_load_dwordx4 v[8:11], v[6:7], off offset:2048
	v_addc_co_u32_e32 v35, vcc, 0, v5, vcc
	v_add_co_u32_e32 v0, vcc, 0x6417000, v4
	s_waitcnt lgkmcnt(0)
	v_mov_b32_e32 v3, v2
	s_nop 1
	v_permlane32_swap_b32_e32 v3, v2
	v_add_f32_e32 v51, v2, v3
	v_addc_co_u32_e32 v1, vcc, 0, v5, vcc
	global_load_dwordx4 v[4:7], v[34:35], off offset:3072
	s_nop 0
	global_load_dwordx4 v[0:3], v[0:1], off
	s_waitcnt lgkmcnt(0)
	v_mov_b32_e32 v54, v51
	s_nop 1
	v_permlane16_swap_b32_e32 v54, v51
	v_add_f32_e32 v34, v51, v54
	s_waitcnt lgkmcnt(0)
	s_nop 1
	v_add_f32_dpp v34, v34, v34 row_mirror row_mask:0xf bank_mask:0xf
	s_waitcnt lgkmcnt(0)
	s_nop 1
	v_add_f32_dpp v34, v34, v34 row_half_mirror row_mask:0xf bank_mask:0xf
	s_waitcnt lgkmcnt(0)
	s_nop 1
	v_add_f32_dpp v34, v34, v34 quad_perm:[2,3,0,1] row_mask:0xf bank_mask:0xf
	s_waitcnt lgkmcnt(0)
	s_nop 1
	v_add_f32_dpp v34, v34, v34 quad_perm:[1,0,3,2] row_mask:0xf bank_mask:0xf
	v_mul_f32_e32 v54, 0x3b000000, v34
	v_pk_add_f32 v[34:35], v[36:37], v[54:55] op_sel_hi:[1,0] neg_lo:[0,1] neg_hi:[0,1]
	v_pk_add_f32 v[36:37], v[38:39], v[54:55] op_sel_hi:[1,0] neg_lo:[0,1] neg_hi:[0,1]
	v_pk_add_f32 v[38:39], v[40:41], v[54:55] op_sel_hi:[1,0] neg_lo:[0,1] neg_hi:[0,1]
	v_pk_add_f32 v[40:41], v[52:53], v[54:55] op_sel_hi:[1,0] neg_lo:[0,1] neg_hi:[0,1]
	v_pk_mul_f32 v[52:53], v[34:35], v[34:35]
	v_pk_mul_f32 v[54:55], v[36:37], v[36:37]
	v_add_f32_e32 v51, v52, v53
	v_add_f32_e32 v51, v54, v51
	v_pk_mul_f32 v[56:57], v[38:39], v[38:39]
	v_add_f32_e32 v51, v55, v51
	v_add_f32_e32 v51, v56, v51
	v_pk_mul_f32 v[58:59], v[40:41], v[40:41]
	v_add_f32_e32 v51, v57, v51
	v_add_f32_e32 v51, v58, v51
	v_add_f32_e32 v51, v59, v51
	s_waitcnt lgkmcnt(0)
	v_mov_b32_e32 v52, v51
	s_nop 1
	v_permlane32_swap_b32_e32 v52, v51
	v_add_f32_e32 v51, v51, v52
	s_waitcnt lgkmcnt(0)
	v_mov_b32_e32 v52, v51
	s_nop 1
	v_permlane16_swap_b32_e32 v52, v51
	v_add_f32_e32 v51, v51, v52
	s_waitcnt lgkmcnt(0)
	s_nop 1
	v_add_f32_dpp v51, v51, v51 row_mirror row_mask:0xf bank_mask:0xf
	s_waitcnt lgkmcnt(0)
	s_nop 1
	v_add_f32_dpp v51, v51, v51 row_half_mirror row_mask:0xf bank_mask:0xf
	s_waitcnt lgkmcnt(0)
	s_nop 1
	v_add_f32_dpp v51, v51, v51 quad_perm:[2,3,0,1] row_mask:0xf bank_mask:0xf
	s_nop 1
	v_add_f32_dpp v51, v51, v51 quad_perm:[1,0,3,2] row_mask:0xf bank_mask:0xf
	s_and_saveexec_b64 s[40:41], s[36:37]
	s_cbranch_execz .LBB0_678
	s_waitcnt lgkmcnt(0)
	v_fmamk_f32 v51, v51, 0x3b000000, v190
	v_mul_f32_e32 v52, 0x4b800000, v51
	v_cmp_gt_f32_e32 vcc, s79, v51
	s_nop 1
	v_cndmask_b32_e32 v51, v51, v52, vcc
	v_rsq_f32_e32 v51, v51
	s_nop 0
	v_mul_f32_e32 v52, 0x45800000, v51
	v_cndmask_b32_e32 v52, v51, v52, vcc
	v_pk_mul_f32 v[34:35], v[34:35], v[52:53] op_sel_hi:[1,0]
	v_pk_mul_f32 v[36:37], v[36:37], v[52:53] op_sel_hi:[1,0]
	v_pk_mul_f32 v[38:39], v[38:39], v[52:53] op_sel_hi:[1,0]
	v_pk_mul_f32 v[40:41], v[40:41], v[52:53] op_sel_hi:[1,0]
	v_bfe_u32 v53, v39, 16, 1
	v_bfe_u32 v51, v41, 16, 1
	v_bfe_u32 v52, v40, 16, 1
	v_bfe_u32 v54, v38, 16, 1
	v_bfe_u32 v55, v37, 16, 1
	v_bfe_u32 v56, v36, 16, 1
	v_bfe_u32 v57, v35, 16, 1
	v_bfe_u32 v58, v34, 16, 1
	v_add3_u32 v34, v34, v58, s94
	v_add3_u32 v57, v35, v57, s94
	v_add3_u32 v35, v36, v56, s94
	v_add3_u32 v55, v37, v55, s94
	v_add3_u32 v36, v38, v54, s94
	v_add3_u32 v38, v39, v53, s94
	v_add3_u32 v37, v40, v52, s94
	v_add3_u32 v39, v41, v51, s94
	v_perm_b32 v37, v39, v37, s95
	v_perm_b32 v36, v38, v36, s95
	v_perm_b32 v35, v55, v35, s95
	v_perm_b32 v34, v57, v34, s95
	ds_write_b128 v50, v[34:37]
.LBB0_678:
	s_or_b64 exec, exec, s[40:41]
	s_waitcnt vmcnt(6)
	v_lshlrev_b32_e32 v34, 16, v24
	v_and_b32_e32 v35, 0xffff0000, v24
	v_add_f32_e32 v24, 0, v34
	v_add_f32_e32 v24, v24, v35
	v_lshlrev_b32_e32 v36, 16, v25
	v_and_b32_e32 v37, 0xffff0000, v25
	v_add_f32_e32 v24, v24, v36
	v_add_f32_e32 v24, v24, v37
	v_lshlrev_b32_e32 v38, 16, v26
	v_and_b32_e32 v39, 0xffff0000, v26
	v_add_f32_e32 v24, v24, v38
	v_add_f32_e32 v24, v24, v39
	v_lshlrev_b32_e32 v40, 16, v27
	v_and_b32_e32 v41, 0xffff0000, v27
	v_add_f32_e32 v24, v24, v40
	v_add_f32_e32 v24, v24, v41
	s_waitcnt lgkmcnt(0)
	v_mov_b32_e32 v25, v24
	s_nop 1
	v_permlane32_swap_b32_e32 v25, v24
	v_add_f32_e32 v24, v24, v25
	s_waitcnt lgkmcnt(0)
	v_mov_b32_e32 v25, v24
	s_nop 1
	v_permlane16_swap_b32_e32 v25, v24
	v_add_f32_e32 v24, v24, v25
	s_waitcnt lgkmcnt(0)
	s_nop 1
	v_add_f32_dpp v24, v24, v24 row_mirror row_mask:0xf bank_mask:0xf
	s_waitcnt lgkmcnt(0)
	s_nop 1
	v_add_f32_dpp v24, v24, v24 row_half_mirror row_mask:0xf bank_mask:0xf
	s_waitcnt lgkmcnt(0)
	s_nop 1
	v_add_f32_dpp v24, v24, v24 quad_perm:[2,3,0,1] row_mask:0xf bank_mask:0xf
	s_waitcnt lgkmcnt(0)
	s_nop 1
	v_add_f32_dpp v24, v24, v24 quad_perm:[1,0,3,2] row_mask:0xf bank_mask:0xf
	v_mul_f32_e32 v52, 0x3b000000, v24
	v_pk_add_f32 v[24:25], v[34:35], v[52:53] op_sel_hi:[1,0] neg_lo:[0,1] neg_hi:[0,1]
	v_pk_add_f32 v[26:27], v[36:37], v[52:53] op_sel_hi:[1,0] neg_lo:[0,1] neg_hi:[0,1]
	v_pk_add_f32 v[34:35], v[38:39], v[52:53] op_sel_hi:[1,0] neg_lo:[0,1] neg_hi:[0,1]
	v_pk_mul_f32 v[38:39], v[24:25], v[24:25]
	v_pk_add_f32 v[36:37], v[40:41], v[52:53] op_sel_hi:[1,0] neg_lo:[0,1] neg_hi:[0,1]
	v_pk_mul_f32 v[40:41], v[26:27], v[26:27]
	v_add_f32_e32 v38, v38, v39
	v_add_f32_e32 v38, v40, v38
	v_pk_mul_f32 v[52:53], v[34:35], v[34:35]
	v_add_f32_e32 v38, v41, v38
	v_add_f32_e32 v38, v52, v38
	v_pk_mul_f32 v[54:55], v[36:37], v[36:37]
	v_add_f32_e32 v38, v53, v38
	v_add_f32_e32 v38, v54, v38
	v_add_f32_e32 v38, v55, v38
	s_waitcnt lgkmcnt(0)
	v_mov_b32_e32 v39, v38
	s_nop 1
	v_permlane32_swap_b32_e32 v39, v38
	v_add_f32_e32 v38, v38, v39
	s_waitcnt lgkmcnt(0)
	v_mov_b32_e32 v39, v38
	s_nop 1
	v_permlane16_swap_b32_e32 v39, v38
	v_add_f32_e32 v38, v38, v39
	s_waitcnt lgkmcnt(0)
	s_nop 1
	v_add_f32_dpp v38, v38, v38 row_mirror row_mask:0xf bank_mask:0xf
	s_waitcnt lgkmcnt(0)
	s_nop 1
	v_add_f32_dpp v38, v38, v38 row_half_mirror row_mask:0xf bank_mask:0xf
	s_waitcnt lgkmcnt(0)
	s_nop 1
	v_add_f32_dpp v38, v38, v38 quad_perm:[2,3,0,1] row_mask:0xf bank_mask:0xf
	s_nop 1
	v_add_f32_dpp v38, v38, v38 quad_perm:[1,0,3,2] row_mask:0xf bank_mask:0xf
	s_and_saveexec_b64 s[40:41], s[36:37]
	s_cbranch_execz .LBB0_680
	s_waitcnt lgkmcnt(0)
	v_fmamk_f32 v38, v38, 0x3b000000, v190
	v_mul_f32_e32 v39, 0x4b800000, v38
	v_cmp_gt_f32_e32 vcc, s79, v38
	s_nop 1
	v_cndmask_b32_e32 v38, v38, v39, vcc
	v_rsq_f32_e32 v38, v38
	s_nop 0
	v_mul_f32_e32 v39, 0x45800000, v38
	v_cndmask_b32_e32 v38, v38, v39, vcc
	v_pk_mul_f32 v[24:25], v[24:25], v[38:39] op_sel_hi:[1,0]
	v_pk_mul_f32 v[26:27], v[26:27], v[38:39] op_sel_hi:[1,0]
	v_pk_mul_f32 v[34:35], v[34:35], v[38:39] op_sel_hi:[1,0]
	v_pk_mul_f32 v[36:37], v[36:37], v[38:39] op_sel_hi:[1,0]
	v_bfe_u32 v40, v35, 16, 1
	v_bfe_u32 v38, v37, 16, 1
	v_bfe_u32 v39, v36, 16, 1
	v_bfe_u32 v41, v34, 16, 1
	v_bfe_u32 v51, v27, 16, 1
	v_bfe_u32 v52, v26, 16, 1
	v_bfe_u32 v53, v25, 16, 1
	v_bfe_u32 v54, v24, 16, 1
	v_add3_u32 v24, v24, v54, s94
	v_add3_u32 v53, v25, v53, s94
	v_add3_u32 v25, v26, v52, s94
	v_add3_u32 v51, v27, v51, s94
	v_add3_u32 v26, v34, v41, s94
	v_add3_u32 v34, v35, v40, s94
	v_add3_u32 v27, v36, v39, s94
	v_add3_u32 v35, v37, v38, s94
	v_perm_b32 v27, v35, v27, s95
	v_perm_b32 v26, v34, v26, s95
	v_perm_b32 v25, v51, v25, s95
	v_perm_b32 v24, v53, v24, s95
	ds_write_b128 v50, v[24:27] offset:288
.LBB0_680:
	s_or_b64 exec, exec, s[40:41]
	s_waitcnt vmcnt(5)
	v_lshlrev_b32_e32 v24, 16, v20
	v_and_b32_e32 v25, 0xffff0000, v20
	v_add_f32_e32 v20, 0, v24
	v_add_f32_e32 v20, v20, v25
	v_lshlrev_b32_e32 v26, 16, v21
	v_and_b32_e32 v27, 0xffff0000, v21
	v_add_f32_e32 v20, v20, v26
	v_add_f32_e32 v20, v20, v27
	v_lshlrev_b32_e32 v34, 16, v22
	v_and_b32_e32 v35, 0xffff0000, v22
	v_add_f32_e32 v20, v20, v34
	v_add_f32_e32 v20, v20, v35
	v_lshlrev_b32_e32 v36, 16, v23
	v_and_b32_e32 v37, 0xffff0000, v23
	v_add_f32_e32 v20, v20, v36
	v_add_f32_e32 v20, v20, v37
	s_waitcnt lgkmcnt(0)
	v_mov_b32_e32 v21, v20
	s_nop 1
	v_permlane32_swap_b32_e32 v21, v20
	v_add_f32_e32 v20, v20, v21
	s_waitcnt lgkmcnt(0)
	v_mov_b32_e32 v21, v20
	s_nop 1
	v_permlane16_swap_b32_e32 v21, v20
	v_add_f32_e32 v20, v20, v21
	s_waitcnt lgkmcnt(0)
	s_nop 1
	v_add_f32_dpp v20, v20, v20 row_mirror row_mask:0xf bank_mask:0xf
	s_waitcnt lgkmcnt(0)
	s_nop 1
	v_add_f32_dpp v20, v20, v20 row_half_mirror row_mask:0xf bank_mask:0xf
	s_waitcnt lgkmcnt(0)
	s_nop 1
	v_add_f32_dpp v20, v20, v20 quad_perm:[2,3,0,1] row_mask:0xf bank_mask:0xf
	s_waitcnt lgkmcnt(0)
	s_nop 1
	v_add_f32_dpp v20, v20, v20 quad_perm:[1,0,3,2] row_mask:0xf bank_mask:0xf
	v_mul_f32_e32 v38, 0x3b000000, v20
	v_pk_add_f32 v[20:21], v[24:25], v[38:39] op_sel_hi:[1,0] neg_lo:[0,1] neg_hi:[0,1]
	v_pk_add_f32 v[22:23], v[26:27], v[38:39] op_sel_hi:[1,0] neg_lo:[0,1] neg_hi:[0,1]
	v_pk_add_f32 v[24:25], v[34:35], v[38:39] op_sel_hi:[1,0] neg_lo:[0,1] neg_hi:[0,1]
	v_pk_mul_f32 v[34:35], v[20:21], v[20:21]
	v_pk_add_f32 v[26:27], v[36:37], v[38:39] op_sel_hi:[1,0] neg_lo:[0,1] neg_hi:[0,1]
	v_pk_mul_f32 v[36:37], v[22:23], v[22:23]
	v_add_f32_e32 v34, v34, v35
	v_add_f32_e32 v34, v36, v34
	v_pk_mul_f32 v[38:39], v[24:25], v[24:25]
	v_add_f32_e32 v34, v37, v34
	v_add_f32_e32 v34, v38, v34
	v_pk_mul_f32 v[40:41], v[26:27], v[26:27]
	v_add_f32_e32 v34, v39, v34
	v_add_f32_e32 v34, v40, v34
	v_add_f32_e32 v34, v41, v34
	s_waitcnt lgkmcnt(0)
	v_mov_b32_e32 v35, v34
	s_nop 1
	v_permlane32_swap_b32_e32 v35, v34
	v_add_f32_e32 v34, v34, v35
	s_waitcnt lgkmcnt(0)
	v_mov_b32_e32 v35, v34
	s_nop 1
	v_permlane16_swap_b32_e32 v35, v34
	v_add_f32_e32 v34, v34, v35
	s_waitcnt lgkmcnt(0)
	s_nop 1
	v_add_f32_dpp v34, v34, v34 row_mirror row_mask:0xf bank_mask:0xf
	s_waitcnt lgkmcnt(0)
	s_nop 1
	v_add_f32_dpp v34, v34, v34 row_half_mirror row_mask:0xf bank_mask:0xf
	s_waitcnt lgkmcnt(0)
	s_nop 1
	v_add_f32_dpp v34, v34, v34 quad_perm:[2,3,0,1] row_mask:0xf bank_mask:0xf
	s_nop 1
	v_add_f32_dpp v34, v34, v34 quad_perm:[1,0,3,2] row_mask:0xf bank_mask:0xf
	s_and_saveexec_b64 s[40:41], s[36:37]
	s_cbranch_execz .LBB0_682
	s_waitcnt lgkmcnt(0)
	v_fmamk_f32 v34, v34, 0x3b000000, v190
	v_mul_f32_e32 v35, 0x4b800000, v34
	v_cmp_gt_f32_e32 vcc, s79, v34
	s_nop 1
	v_cndmask_b32_e32 v34, v34, v35, vcc
	v_rsq_f32_e32 v34, v34
	s_nop 0
	v_mul_f32_e32 v35, 0x45800000, v34
	v_cndmask_b32_e32 v34, v34, v35, vcc
	v_pk_mul_f32 v[20:21], v[20:21], v[34:35] op_sel_hi:[1,0]
	v_pk_mul_f32 v[22:23], v[22:23], v[34:35] op_sel_hi:[1,0]
	v_pk_mul_f32 v[24:25], v[24:25], v[34:35] op_sel_hi:[1,0]
	v_pk_mul_f32 v[26:27], v[26:27], v[34:35] op_sel_hi:[1,0]
	v_bfe_u32 v36, v25, 16, 1
	v_bfe_u32 v34, v27, 16, 1
	v_bfe_u32 v35, v26, 16, 1
	v_bfe_u32 v37, v24, 16, 1
	v_bfe_u32 v38, v23, 16, 1
	v_bfe_u32 v39, v22, 16, 1
	v_bfe_u32 v40, v21, 16, 1
	v_bfe_u32 v41, v20, 16, 1
	v_add3_u32 v20, v20, v41, s94
	v_add3_u32 v40, v21, v40, s94
	v_add3_u32 v21, v22, v39, s94
	v_add3_u32 v38, v23, v38, s94
	v_add3_u32 v22, v24, v37, s94
	v_add3_u32 v24, v25, v36, s94
	v_add3_u32 v23, v26, v35, s94
	v_add3_u32 v25, v27, v34, s94
	v_perm_b32 v23, v25, v23, s95
	v_perm_b32 v22, v24, v22, s95
	v_perm_b32 v21, v38, v21, s95
	v_perm_b32 v20, v40, v20, s95
	ds_write_b128 v50, v[20:23] offset:576
.LBB0_682:
	s_or_b64 exec, exec, s[40:41]
	s_waitcnt vmcnt(4)
	v_lshlrev_b32_e32 v20, 16, v16
	v_and_b32_e32 v21, 0xffff0000, v16
	v_add_f32_e32 v16, 0, v20
	v_add_f32_e32 v16, v16, v21
	v_lshlrev_b32_e32 v22, 16, v17
	v_and_b32_e32 v23, 0xffff0000, v17
	v_add_f32_e32 v16, v16, v22
	v_add_f32_e32 v16, v16, v23
	v_lshlrev_b32_e32 v24, 16, v18
	v_and_b32_e32 v25, 0xffff0000, v18
	v_add_f32_e32 v16, v16, v24
	v_add_f32_e32 v16, v16, v25
	v_lshlrev_b32_e32 v26, 16, v19
	v_and_b32_e32 v27, 0xffff0000, v19
	v_add_f32_e32 v16, v16, v26
	v_add_f32_e32 v16, v16, v27
	s_waitcnt lgkmcnt(0)
	v_mov_b32_e32 v17, v16
	s_nop 1
	v_permlane32_swap_b32_e32 v17, v16
	v_add_f32_e32 v16, v16, v17
	s_waitcnt lgkmcnt(0)
	v_mov_b32_e32 v17, v16
	s_nop 1
	v_permlane16_swap_b32_e32 v17, v16
	v_add_f32_e32 v16, v16, v17
	s_waitcnt lgkmcnt(0)
	s_nop 1
	v_add_f32_dpp v16, v16, v16 row_mirror row_mask:0xf bank_mask:0xf
	s_waitcnt lgkmcnt(0)
	s_nop 1
	v_add_f32_dpp v16, v16, v16 row_half_mirror row_mask:0xf bank_mask:0xf
	s_waitcnt lgkmcnt(0)
	s_nop 1
	v_add_f32_dpp v16, v16, v16 quad_perm:[2,3,0,1] row_mask:0xf bank_mask:0xf
	s_waitcnt lgkmcnt(0)
	s_nop 1
	v_add_f32_dpp v16, v16, v16 quad_perm:[1,0,3,2] row_mask:0xf bank_mask:0xf
	v_mul_f32_e32 v34, 0x3b000000, v16
	v_pk_add_f32 v[16:17], v[20:21], v[34:35] op_sel_hi:[1,0] neg_lo:[0,1] neg_hi:[0,1]
	v_pk_add_f32 v[18:19], v[22:23], v[34:35] op_sel_hi:[1,0] neg_lo:[0,1] neg_hi:[0,1]
	v_pk_add_f32 v[20:21], v[24:25], v[34:35] op_sel_hi:[1,0] neg_lo:[0,1] neg_hi:[0,1]
	v_pk_mul_f32 v[24:25], v[16:17], v[16:17]
	v_pk_add_f32 v[22:23], v[26:27], v[34:35] op_sel_hi:[1,0] neg_lo:[0,1] neg_hi:[0,1]
	v_pk_mul_f32 v[26:27], v[18:19], v[18:19]
	v_add_f32_e32 v24, v24, v25
	v_add_f32_e32 v24, v26, v24
	v_pk_mul_f32 v[34:35], v[20:21], v[20:21]
	v_add_f32_e32 v24, v27, v24
	v_add_f32_e32 v24, v34, v24
	v_pk_mul_f32 v[36:37], v[22:23], v[22:23]
	v_add_f32_e32 v24, v35, v24
	v_add_f32_e32 v24, v36, v24
	v_add_f32_e32 v24, v37, v24
	s_waitcnt lgkmcnt(0)
	v_mov_b32_e32 v25, v24
	s_nop 1
	v_permlane32_swap_b32_e32 v25, v24
	v_add_f32_e32 v24, v24, v25
	s_waitcnt lgkmcnt(0)
	v_mov_b32_e32 v25, v24
	s_nop 1
	v_permlane16_swap_b32_e32 v25, v24
	v_add_f32_e32 v24, v24, v25
	s_waitcnt lgkmcnt(0)
	s_nop 1
	v_add_f32_dpp v24, v24, v24 row_mirror row_mask:0xf bank_mask:0xf
	s_waitcnt lgkmcnt(0)
	s_nop 1
	v_add_f32_dpp v24, v24, v24 row_half_mirror row_mask:0xf bank_mask:0xf
	s_waitcnt lgkmcnt(0)
	s_nop 1
	v_add_f32_dpp v24, v24, v24 quad_perm:[2,3,0,1] row_mask:0xf bank_mask:0xf
	s_nop 1
	v_add_f32_dpp v24, v24, v24 quad_perm:[1,0,3,2] row_mask:0xf bank_mask:0xf
	s_and_saveexec_b64 s[40:41], s[36:37]
	s_cbranch_execz .LBB0_684
	s_waitcnt lgkmcnt(0)
	v_fmamk_f32 v24, v24, 0x3b000000, v190
	v_mul_f32_e32 v25, 0x4b800000, v24
	v_cmp_gt_f32_e32 vcc, s79, v24
	s_nop 1
	v_cndmask_b32_e32 v24, v24, v25, vcc
	v_rsq_f32_e32 v24, v24
	s_nop 0
	v_mul_f32_e32 v25, 0x45800000, v24
	v_cndmask_b32_e32 v24, v24, v25, vcc
	v_pk_mul_f32 v[16:17], v[16:17], v[24:25] op_sel_hi:[1,0]
	v_pk_mul_f32 v[18:19], v[18:19], v[24:25] op_sel_hi:[1,0]
	v_pk_mul_f32 v[20:21], v[20:21], v[24:25] op_sel_hi:[1,0]
	v_pk_mul_f32 v[22:23], v[22:23], v[24:25] op_sel_hi:[1,0]
	v_bfe_u32 v26, v21, 16, 1
	v_bfe_u32 v24, v23, 16, 1
	v_bfe_u32 v25, v22, 16, 1
	v_bfe_u32 v27, v20, 16, 1
	v_bfe_u32 v34, v19, 16, 1
	v_bfe_u32 v35, v18, 16, 1
	v_bfe_u32 v36, v17, 16, 1
	v_bfe_u32 v37, v16, 16, 1
	v_add3_u32 v16, v16, v37, s94
	v_add3_u32 v36, v17, v36, s94
	v_add3_u32 v17, v18, v35, s94
	v_add3_u32 v34, v19, v34, s94
	v_add3_u32 v18, v20, v27, s94
	v_add3_u32 v20, v21, v26, s94
	v_add3_u32 v19, v22, v25, s94
	v_add3_u32 v21, v23, v24, s94
	v_perm_b32 v19, v21, v19, s95
	v_perm_b32 v18, v20, v18, s95
	v_perm_b32 v17, v34, v17, s95
	v_perm_b32 v16, v36, v16, s95
	ds_write_b128 v50, v[16:19] offset:864
.LBB0_684:
	s_or_b64 exec, exec, s[40:41]
	s_waitcnt vmcnt(3)
	v_lshlrev_b32_e32 v16, 16, v12
	v_and_b32_e32 v17, 0xffff0000, v12
	v_add_f32_e32 v12, 0, v16
	v_add_f32_e32 v12, v12, v17
	v_lshlrev_b32_e32 v18, 16, v13
	v_and_b32_e32 v19, 0xffff0000, v13
	v_add_f32_e32 v12, v12, v18
	v_add_f32_e32 v12, v12, v19
	v_lshlrev_b32_e32 v20, 16, v14
	v_and_b32_e32 v21, 0xffff0000, v14
	v_add_f32_e32 v12, v12, v20
	v_add_f32_e32 v12, v12, v21
	v_lshlrev_b32_e32 v22, 16, v15
	v_and_b32_e32 v23, 0xffff0000, v15
	v_add_f32_e32 v12, v12, v22
	v_add_f32_e32 v12, v12, v23
	s_waitcnt lgkmcnt(0)
	v_mov_b32_e32 v13, v12
	s_nop 1
	v_permlane32_swap_b32_e32 v13, v12
	v_add_f32_e32 v12, v12, v13
	s_waitcnt lgkmcnt(0)
	v_mov_b32_e32 v13, v12
	s_nop 1
	v_permlane16_swap_b32_e32 v13, v12
	v_add_f32_e32 v12, v12, v13
	s_waitcnt lgkmcnt(0)
	s_nop 1
	v_add_f32_dpp v12, v12, v12 row_mirror row_mask:0xf bank_mask:0xf
	s_waitcnt lgkmcnt(0)
	s_nop 1
	v_add_f32_dpp v12, v12, v12 row_half_mirror row_mask:0xf bank_mask:0xf
	s_waitcnt lgkmcnt(0)
	s_nop 1
	v_add_f32_dpp v12, v12, v12 quad_perm:[2,3,0,1] row_mask:0xf bank_mask:0xf
	s_waitcnt lgkmcnt(0)
	s_nop 1
	v_add_f32_dpp v12, v12, v12 quad_perm:[1,0,3,2] row_mask:0xf bank_mask:0xf
	v_mul_f32_e32 v24, 0x3b000000, v12
	v_pk_add_f32 v[12:13], v[16:17], v[24:25] op_sel_hi:[1,0] neg_lo:[0,1] neg_hi:[0,1]
	v_pk_add_f32 v[14:15], v[18:19], v[24:25] op_sel_hi:[1,0] neg_lo:[0,1] neg_hi:[0,1]
	v_pk_add_f32 v[16:17], v[20:21], v[24:25] op_sel_hi:[1,0] neg_lo:[0,1] neg_hi:[0,1]
	v_pk_mul_f32 v[20:21], v[12:13], v[12:13]
	v_pk_add_f32 v[18:19], v[22:23], v[24:25] op_sel_hi:[1,0] neg_lo:[0,1] neg_hi:[0,1]
	v_pk_mul_f32 v[22:23], v[14:15], v[14:15]
	v_add_f32_e32 v20, v20, v21
	v_add_f32_e32 v20, v22, v20
	v_pk_mul_f32 v[24:25], v[16:17], v[16:17]
	v_add_f32_e32 v20, v23, v20
	v_add_f32_e32 v20, v24, v20
	v_pk_mul_f32 v[26:27], v[18:19], v[18:19]
	v_add_f32_e32 v20, v25, v20
	v_add_f32_e32 v20, v26, v20
	v_add_f32_e32 v20, v27, v20
	s_waitcnt lgkmcnt(0)
	v_mov_b32_e32 v21, v20
	s_nop 1
	v_permlane32_swap_b32_e32 v21, v20
	v_add_f32_e32 v20, v20, v21
	s_waitcnt lgkmcnt(0)
	v_mov_b32_e32 v21, v20
	s_nop 1
	v_permlane16_swap_b32_e32 v21, v20
	v_add_f32_e32 v20, v20, v21
	s_waitcnt lgkmcnt(0)
	s_nop 1
	v_add_f32_dpp v20, v20, v20 row_mirror row_mask:0xf bank_mask:0xf
	s_waitcnt lgkmcnt(0)
	s_nop 1
	v_add_f32_dpp v20, v20, v20 row_half_mirror row_mask:0xf bank_mask:0xf
	s_waitcnt lgkmcnt(0)
	s_nop 1
	v_add_f32_dpp v20, v20, v20 quad_perm:[2,3,0,1] row_mask:0xf bank_mask:0xf
	s_nop 1
	v_add_f32_dpp v20, v20, v20 quad_perm:[1,0,3,2] row_mask:0xf bank_mask:0xf
	s_and_saveexec_b64 s[40:41], s[36:37]
	s_cbranch_execz .LBB0_686
	s_waitcnt lgkmcnt(0)
	v_fmamk_f32 v20, v20, 0x3b000000, v190
	v_mul_f32_e32 v21, 0x4b800000, v20
	v_cmp_gt_f32_e32 vcc, s79, v20
	s_nop 1
	v_cndmask_b32_e32 v20, v20, v21, vcc
	v_rsq_f32_e32 v20, v20
	s_nop 0
	v_mul_f32_e32 v21, 0x45800000, v20
	v_cndmask_b32_e32 v20, v20, v21, vcc
	v_pk_mul_f32 v[12:13], v[12:13], v[20:21] op_sel_hi:[1,0]
	v_pk_mul_f32 v[14:15], v[14:15], v[20:21] op_sel_hi:[1,0]
	v_pk_mul_f32 v[16:17], v[16:17], v[20:21] op_sel_hi:[1,0]
	v_pk_mul_f32 v[18:19], v[18:19], v[20:21] op_sel_hi:[1,0]
	v_bfe_u32 v22, v17, 16, 1
	v_bfe_u32 v20, v19, 16, 1
	v_bfe_u32 v21, v18, 16, 1
	v_bfe_u32 v23, v16, 16, 1
	v_bfe_u32 v24, v15, 16, 1
	v_bfe_u32 v25, v14, 16, 1
	v_bfe_u32 v26, v13, 16, 1
	v_bfe_u32 v27, v12, 16, 1
	v_add3_u32 v12, v12, v27, s94
	v_add3_u32 v26, v13, v26, s94
	v_add3_u32 v13, v14, v25, s94
	v_add3_u32 v24, v15, v24, s94
	v_add3_u32 v14, v16, v23, s94
	v_add3_u32 v16, v17, v22, s94
	v_add3_u32 v15, v18, v21, s94
	v_add3_u32 v17, v19, v20, s94
	v_perm_b32 v15, v17, v15, s95
	v_perm_b32 v14, v16, v14, s95
	v_perm_b32 v13, v24, v13, s95
	v_perm_b32 v12, v26, v12, s95
	ds_write_b128 v50, v[12:15] offset:1152
.LBB0_686:
	s_or_b64 exec, exec, s[40:41]
	s_waitcnt vmcnt(2)
	v_lshlrev_b32_e32 v12, 16, v8
	v_and_b32_e32 v13, 0xffff0000, v8
	v_add_f32_e32 v8, 0, v12
	v_add_f32_e32 v8, v8, v13
	v_lshlrev_b32_e32 v14, 16, v9
	v_and_b32_e32 v15, 0xffff0000, v9
	v_add_f32_e32 v8, v8, v14
	v_add_f32_e32 v8, v8, v15
	v_lshlrev_b32_e32 v16, 16, v10
	v_and_b32_e32 v17, 0xffff0000, v10
	v_add_f32_e32 v8, v8, v16
	v_add_f32_e32 v8, v8, v17
	v_lshlrev_b32_e32 v18, 16, v11
	v_and_b32_e32 v19, 0xffff0000, v11
	v_add_f32_e32 v8, v8, v18
	v_add_f32_e32 v8, v8, v19
	s_waitcnt lgkmcnt(0)
	v_mov_b32_e32 v9, v8
	s_nop 1
	v_permlane32_swap_b32_e32 v9, v8
	v_add_f32_e32 v8, v8, v9
	s_waitcnt lgkmcnt(0)
	v_mov_b32_e32 v9, v8
	s_nop 1
	v_permlane16_swap_b32_e32 v9, v8
	v_add_f32_e32 v8, v8, v9
	s_waitcnt lgkmcnt(0)
	s_nop 1
	v_add_f32_dpp v8, v8, v8 row_mirror row_mask:0xf bank_mask:0xf
	s_waitcnt lgkmcnt(0)
	s_nop 1
	v_add_f32_dpp v8, v8, v8 row_half_mirror row_mask:0xf bank_mask:0xf
	s_waitcnt lgkmcnt(0)
	s_nop 1
	v_add_f32_dpp v8, v8, v8 quad_perm:[2,3,0,1] row_mask:0xf bank_mask:0xf
	s_waitcnt lgkmcnt(0)
	s_nop 1
	v_add_f32_dpp v8, v8, v8 quad_perm:[1,0,3,2] row_mask:0xf bank_mask:0xf
	v_mul_f32_e32 v20, 0x3b000000, v8
	v_pk_add_f32 v[8:9], v[12:13], v[20:21] op_sel_hi:[1,0] neg_lo:[0,1] neg_hi:[0,1]
	v_pk_add_f32 v[10:11], v[14:15], v[20:21] op_sel_hi:[1,0] neg_lo:[0,1] neg_hi:[0,1]
	v_pk_add_f32 v[12:13], v[16:17], v[20:21] op_sel_hi:[1,0] neg_lo:[0,1] neg_hi:[0,1]
	v_pk_mul_f32 v[16:17], v[8:9], v[8:9]
	v_pk_add_f32 v[14:15], v[18:19], v[20:21] op_sel_hi:[1,0] neg_lo:[0,1] neg_hi:[0,1]
	v_pk_mul_f32 v[18:19], v[10:11], v[10:11]
	v_add_f32_e32 v16, v16, v17
	v_add_f32_e32 v16, v18, v16
	v_pk_mul_f32 v[20:21], v[12:13], v[12:13]
	v_add_f32_e32 v16, v19, v16
	v_add_f32_e32 v16, v20, v16
	v_pk_mul_f32 v[22:23], v[14:15], v[14:15]
	v_add_f32_e32 v16, v21, v16
	v_add_f32_e32 v16, v22, v16
	v_add_f32_e32 v16, v23, v16
	s_waitcnt lgkmcnt(0)
	v_mov_b32_e32 v17, v16
	s_nop 1
	v_permlane32_swap_b32_e32 v17, v16
	v_add_f32_e32 v16, v16, v17
	s_waitcnt lgkmcnt(0)
	v_mov_b32_e32 v17, v16
	s_nop 1
	v_permlane16_swap_b32_e32 v17, v16
	v_add_f32_e32 v16, v16, v17
	s_waitcnt lgkmcnt(0)
	s_nop 1
	v_add_f32_dpp v16, v16, v16 row_mirror row_mask:0xf bank_mask:0xf
	s_waitcnt lgkmcnt(0)
	s_nop 1
	v_add_f32_dpp v16, v16, v16 row_half_mirror row_mask:0xf bank_mask:0xf
	s_waitcnt lgkmcnt(0)
	s_nop 1
	v_add_f32_dpp v16, v16, v16 quad_perm:[2,3,0,1] row_mask:0xf bank_mask:0xf
	s_nop 1
	v_add_f32_dpp v16, v16, v16 quad_perm:[1,0,3,2] row_mask:0xf bank_mask:0xf
	s_and_saveexec_b64 s[40:41], s[36:37]
	s_cbranch_execz .LBB0_688
	s_waitcnt lgkmcnt(0)
	v_fmamk_f32 v16, v16, 0x3b000000, v190
	v_mul_f32_e32 v17, 0x4b800000, v16
	v_cmp_gt_f32_e32 vcc, s79, v16
	s_nop 1
	v_cndmask_b32_e32 v16, v16, v17, vcc
	v_rsq_f32_e32 v16, v16
	s_nop 0
	v_mul_f32_e32 v17, 0x45800000, v16
	v_cndmask_b32_e32 v16, v16, v17, vcc
	v_pk_mul_f32 v[8:9], v[8:9], v[16:17] op_sel_hi:[1,0]
	v_pk_mul_f32 v[10:11], v[10:11], v[16:17] op_sel_hi:[1,0]
	v_pk_mul_f32 v[12:13], v[12:13], v[16:17] op_sel_hi:[1,0]
	v_pk_mul_f32 v[14:15], v[14:15], v[16:17] op_sel_hi:[1,0]
	v_bfe_u32 v18, v13, 16, 1
	v_bfe_u32 v16, v15, 16, 1
	v_bfe_u32 v17, v14, 16, 1
	v_bfe_u32 v19, v12, 16, 1
	v_bfe_u32 v20, v11, 16, 1
	v_bfe_u32 v21, v10, 16, 1
	v_bfe_u32 v22, v9, 16, 1
	v_bfe_u32 v23, v8, 16, 1
	v_add3_u32 v8, v8, v23, s94
	v_add3_u32 v22, v9, v22, s94
	v_add3_u32 v9, v10, v21, s94
	v_add3_u32 v20, v11, v20, s94
	v_add3_u32 v10, v12, v19, s94
	v_add3_u32 v12, v13, v18, s94
	v_add3_u32 v11, v14, v17, s94
	v_add3_u32 v13, v15, v16, s94
	v_perm_b32 v11, v13, v11, s95
	v_perm_b32 v10, v12, v10, s95
	v_perm_b32 v9, v20, v9, s95
	v_perm_b32 v8, v22, v8, s95
	ds_write_b128 v50, v[8:11] offset:1440
.LBB0_688:
	s_or_b64 exec, exec, s[40:41]
	s_waitcnt vmcnt(1)
	v_lshlrev_b32_e32 v8, 16, v4
	v_and_b32_e32 v9, 0xffff0000, v4
	v_add_f32_e32 v4, 0, v8
	v_add_f32_e32 v4, v4, v9
	v_lshlrev_b32_e32 v10, 16, v5
	v_and_b32_e32 v11, 0xffff0000, v5
	v_add_f32_e32 v4, v4, v10
	v_add_f32_e32 v4, v4, v11
	v_lshlrev_b32_e32 v12, 16, v6
	v_and_b32_e32 v13, 0xffff0000, v6
	v_add_f32_e32 v4, v4, v12
	v_add_f32_e32 v4, v4, v13
	v_lshlrev_b32_e32 v14, 16, v7
	v_and_b32_e32 v15, 0xffff0000, v7
	v_add_f32_e32 v4, v4, v14
	v_add_f32_e32 v4, v4, v15
	s_waitcnt lgkmcnt(0)
	v_mov_b32_e32 v5, v4
	s_nop 1
	v_permlane32_swap_b32_e32 v5, v4
	v_add_f32_e32 v4, v4, v5
	s_waitcnt lgkmcnt(0)
	v_mov_b32_e32 v5, v4
	s_nop 1
	v_permlane16_swap_b32_e32 v5, v4
	v_add_f32_e32 v4, v4, v5
	s_waitcnt lgkmcnt(0)
	s_nop 1
	v_add_f32_dpp v4, v4, v4 row_mirror row_mask:0xf bank_mask:0xf
	s_waitcnt lgkmcnt(0)
	s_nop 1
	v_add_f32_dpp v4, v4, v4 row_half_mirror row_mask:0xf bank_mask:0xf
	s_waitcnt lgkmcnt(0)
	s_nop 1
	v_add_f32_dpp v4, v4, v4 quad_perm:[2,3,0,1] row_mask:0xf bank_mask:0xf
	s_waitcnt lgkmcnt(0)
	s_nop 1
	v_add_f32_dpp v4, v4, v4 quad_perm:[1,0,3,2] row_mask:0xf bank_mask:0xf
	v_mul_f32_e32 v16, 0x3b000000, v4
	v_pk_add_f32 v[4:5], v[8:9], v[16:17] op_sel_hi:[1,0] neg_lo:[0,1] neg_hi:[0,1]
	v_pk_add_f32 v[6:7], v[10:11], v[16:17] op_sel_hi:[1,0] neg_lo:[0,1] neg_hi:[0,1]
	v_pk_add_f32 v[8:9], v[12:13], v[16:17] op_sel_hi:[1,0] neg_lo:[0,1] neg_hi:[0,1]
	v_pk_mul_f32 v[12:13], v[4:5], v[4:5]
	v_pk_add_f32 v[10:11], v[14:15], v[16:17] op_sel_hi:[1,0] neg_lo:[0,1] neg_hi:[0,1]
	v_pk_mul_f32 v[14:15], v[6:7], v[6:7]
	v_add_f32_e32 v12, v12, v13
	v_add_f32_e32 v12, v14, v12
	v_pk_mul_f32 v[16:17], v[8:9], v[8:9]
	v_add_f32_e32 v12, v15, v12
	v_add_f32_e32 v12, v16, v12
	v_pk_mul_f32 v[18:19], v[10:11], v[10:11]
	v_add_f32_e32 v12, v17, v12
	v_add_f32_e32 v12, v18, v12
	v_add_f32_e32 v12, v19, v12
	s_waitcnt lgkmcnt(0)
	v_mov_b32_e32 v13, v12
	s_nop 1
	v_permlane32_swap_b32_e32 v13, v12
	v_add_f32_e32 v12, v12, v13
	s_waitcnt lgkmcnt(0)
	v_mov_b32_e32 v13, v12
	s_nop 1
	v_permlane16_swap_b32_e32 v13, v12
	v_add_f32_e32 v12, v12, v13
	s_waitcnt lgkmcnt(0)
	s_nop 1
	v_add_f32_dpp v12, v12, v12 row_mirror row_mask:0xf bank_mask:0xf
	s_waitcnt lgkmcnt(0)
	s_nop 1
	v_add_f32_dpp v12, v12, v12 row_half_mirror row_mask:0xf bank_mask:0xf
	s_waitcnt lgkmcnt(0)
	s_nop 1
	v_add_f32_dpp v12, v12, v12 quad_perm:[2,3,0,1] row_mask:0xf bank_mask:0xf
	s_nop 1
	v_add_f32_dpp v12, v12, v12 quad_perm:[1,0,3,2] row_mask:0xf bank_mask:0xf
	s_and_saveexec_b64 s[40:41], s[36:37]
	s_cbranch_execz .LBB0_690
	s_waitcnt lgkmcnt(0)
	v_fmamk_f32 v12, v12, 0x3b000000, v190
	v_mul_f32_e32 v13, 0x4b800000, v12
	v_cmp_gt_f32_e32 vcc, s79, v12
	s_nop 1
	v_cndmask_b32_e32 v12, v12, v13, vcc
	v_rsq_f32_e32 v12, v12
	s_nop 0
	v_mul_f32_e32 v13, 0x45800000, v12
	v_cndmask_b32_e32 v12, v12, v13, vcc
	v_pk_mul_f32 v[4:5], v[4:5], v[12:13] op_sel_hi:[1,0]
	v_pk_mul_f32 v[6:7], v[6:7], v[12:13] op_sel_hi:[1,0]
	v_pk_mul_f32 v[8:9], v[8:9], v[12:13] op_sel_hi:[1,0]
	v_pk_mul_f32 v[10:11], v[10:11], v[12:13] op_sel_hi:[1,0]
	v_bfe_u32 v14, v9, 16, 1
	v_bfe_u32 v12, v11, 16, 1
	v_bfe_u32 v13, v10, 16, 1
	v_bfe_u32 v15, v8, 16, 1
	v_bfe_u32 v16, v7, 16, 1
	v_bfe_u32 v17, v6, 16, 1
	v_bfe_u32 v18, v5, 16, 1
	v_bfe_u32 v19, v4, 16, 1
	v_add3_u32 v4, v4, v19, s94
	v_add3_u32 v18, v5, v18, s94
	v_add3_u32 v5, v6, v17, s94
	v_add3_u32 v16, v7, v16, s94
	v_add3_u32 v6, v8, v15, s94
	v_add3_u32 v8, v9, v14, s94
	v_add3_u32 v7, v10, v13, s94
	v_add3_u32 v9, v11, v12, s94
	v_perm_b32 v7, v9, v7, s95
	v_perm_b32 v6, v8, v6, s95
	v_perm_b32 v5, v16, v5, s95
	v_perm_b32 v4, v18, v4, s95
	ds_write_b128 v50, v[4:7] offset:1728
.LBB0_690:
	s_or_b64 exec, exec, s[40:41]
	s_waitcnt vmcnt(0)
	v_lshlrev_b32_e32 v4, 16, v0
	v_and_b32_e32 v5, 0xffff0000, v0
	v_add_f32_e32 v0, 0, v4
	v_add_f32_e32 v0, v0, v5
	v_lshlrev_b32_e32 v6, 16, v1
	v_and_b32_e32 v7, 0xffff0000, v1
	v_add_f32_e32 v0, v0, v6
	v_add_f32_e32 v0, v0, v7
	v_lshlrev_b32_e32 v8, 16, v2
	v_and_b32_e32 v9, 0xffff0000, v2
	v_add_f32_e32 v0, v0, v8
	v_add_f32_e32 v0, v0, v9
	v_lshlrev_b32_e32 v10, 16, v3
	v_and_b32_e32 v11, 0xffff0000, v3
	v_add_f32_e32 v0, v0, v10
	v_add_f32_e32 v0, v0, v11
	s_waitcnt lgkmcnt(0)
	v_mov_b32_e32 v1, v0
	s_nop 1
	v_permlane32_swap_b32_e32 v1, v0
	v_add_f32_e32 v0, v0, v1
	s_waitcnt lgkmcnt(0)
	v_mov_b32_e32 v1, v0
	s_nop 1
	v_permlane16_swap_b32_e32 v1, v0
	v_add_f32_e32 v0, v0, v1
	s_waitcnt lgkmcnt(0)
	s_nop 1
	v_add_f32_dpp v0, v0, v0 row_mirror row_mask:0xf bank_mask:0xf
	s_waitcnt lgkmcnt(0)
	s_nop 1
	v_add_f32_dpp v0, v0, v0 row_half_mirror row_mask:0xf bank_mask:0xf
	s_waitcnt lgkmcnt(0)
	s_nop 1
	v_add_f32_dpp v0, v0, v0 quad_perm:[2,3,0,1] row_mask:0xf bank_mask:0xf
	s_waitcnt lgkmcnt(0)
	s_nop 1
	v_add_f32_dpp v0, v0, v0 quad_perm:[1,0,3,2] row_mask:0xf bank_mask:0xf
	v_mul_f32_e32 v12, 0x3b000000, v0
	v_pk_add_f32 v[0:1], v[4:5], v[12:13] op_sel_hi:[1,0] neg_lo:[0,1] neg_hi:[0,1]
	v_pk_add_f32 v[2:3], v[6:7], v[12:13] op_sel_hi:[1,0] neg_lo:[0,1] neg_hi:[0,1]
	v_pk_add_f32 v[4:5], v[8:9], v[12:13] op_sel_hi:[1,0] neg_lo:[0,1] neg_hi:[0,1]
	v_pk_mul_f32 v[8:9], v[0:1], v[0:1]
	v_pk_add_f32 v[6:7], v[10:11], v[12:13] op_sel_hi:[1,0] neg_lo:[0,1] neg_hi:[0,1]
	v_pk_mul_f32 v[10:11], v[2:3], v[2:3]
	v_add_f32_e32 v8, v8, v9
	v_add_f32_e32 v8, v10, v8
	v_pk_mul_f32 v[12:13], v[4:5], v[4:5]
	v_add_f32_e32 v8, v11, v8
	v_add_f32_e32 v8, v12, v8
	v_pk_mul_f32 v[14:15], v[6:7], v[6:7]
	v_add_f32_e32 v8, v13, v8
	v_add_f32_e32 v8, v14, v8
	v_add_f32_e32 v8, v15, v8
	s_waitcnt lgkmcnt(0)
	v_mov_b32_e32 v9, v8
	s_nop 1
	v_permlane32_swap_b32_e32 v9, v8
	v_add_f32_e32 v8, v8, v9
	s_waitcnt lgkmcnt(0)
	v_mov_b32_e32 v9, v8
	s_nop 1
	v_permlane16_swap_b32_e32 v9, v8
	v_add_f32_e32 v8, v8, v9
	s_waitcnt lgkmcnt(0)
	s_nop 1
	v_add_f32_dpp v8, v8, v8 row_mirror row_mask:0xf bank_mask:0xf
	s_waitcnt lgkmcnt(0)
	s_nop 1
	v_add_f32_dpp v8, v8, v8 row_half_mirror row_mask:0xf bank_mask:0xf
	s_waitcnt lgkmcnt(0)
	s_nop 1
	v_add_f32_dpp v8, v8, v8 quad_perm:[2,3,0,1] row_mask:0xf bank_mask:0xf
	s_nop 1
	v_add_f32_dpp v8, v8, v8 quad_perm:[1,0,3,2] row_mask:0xf bank_mask:0xf
	s_and_saveexec_b64 s[40:41], s[36:37]
	s_cbranch_execz .LBB0_675
	s_waitcnt lgkmcnt(0)
	v_fmamk_f32 v8, v8, 0x3b000000, v190
	v_mul_f32_e32 v9, 0x4b800000, v8
	v_cmp_gt_f32_e32 vcc, s79, v8
	s_nop 1
	v_cndmask_b32_e32 v8, v8, v9, vcc
	v_rsq_f32_e32 v8, v8
	s_nop 0
	v_mul_f32_e32 v9, 0x45800000, v8
	v_cndmask_b32_e32 v8, v8, v9, vcc
	v_pk_mul_f32 v[0:1], v[0:1], v[8:9] op_sel_hi:[1,0]
	v_pk_mul_f32 v[2:3], v[2:3], v[8:9] op_sel_hi:[1,0]
	v_pk_mul_f32 v[4:5], v[4:5], v[8:9] op_sel_hi:[1,0]
	v_pk_mul_f32 v[6:7], v[6:7], v[8:9] op_sel_hi:[1,0]
	v_bfe_u32 v10, v5, 16, 1
	v_bfe_u32 v8, v7, 16, 1
	v_bfe_u32 v9, v6, 16, 1
	v_bfe_u32 v11, v4, 16, 1
	v_bfe_u32 v12, v3, 16, 1
	v_bfe_u32 v13, v2, 16, 1
	v_bfe_u32 v14, v1, 16, 1
	v_bfe_u32 v15, v0, 16, 1
	v_add3_u32 v0, v0, v15, s94
	v_add3_u32 v14, v1, v14, s94
	v_add3_u32 v1, v2, v13, s94
	v_add3_u32 v12, v3, v12, s94
	v_add3_u32 v2, v4, v11, s94
	v_add3_u32 v4, v5, v10, s94
	v_add3_u32 v3, v6, v9, s94
	v_add3_u32 v5, v7, v8, s94
	v_perm_b32 v3, v5, v3, s95
	v_perm_b32 v2, v4, v2, s95
	v_perm_b32 v1, v12, v1, s95
	v_perm_b32 v0, v14, v0, s95
	ds_write_b128 v50, v[0:3] offset:2016
	s_branch .LBB0_675
